# GEMM-3 K-step order rotated per CU (start k from HW cu_id) to spread weight-line reads
# baseline (speedup 1.0000x reference)
.LBB0_345:
	v_and_b32_e32 v246, 63, v208
	v_lshrrev_b32_e32 v247, 6, v208
	v_lshrrev_b32_e32 v248, 3, v246
	v_and_b32_e32 v249, 7, v246
	v_xor_b32_e32 v249, v249, v248
	v_lshlrev_b32_e32 v249, 4, v249
	v_lshl_add_u32 v250, v247, 5, v248
	v_lshl_add_u32 v234, v250, 11, v249
	v_add_u32_e32 v235, 0x4000, v234
	v_add_u32_e32 v236, 0x8000, v234
	v_add_u32_e32 v237, 0xc000, v234
	v_lshlrev_b32_e32 v238, 4, v246
	v_add_u32_e32 v239, 0x8000, v238
	v_add_u32_e32 v240, 0x10000, v238
	v_add_u32_e32 v241, 0x18000, v238
	v_readfirstlane_b32 s2, v247
	s_lshl_b32 s20, s2, 12
	v_and_b32_e32 v251, 15, v246
	v_lshrrev_b32_e32 v252, 4, v246
	v_and_b32_e32 v253, 7, v251
	v_xor_b32_e32 v253, v253, v252
	v_lshlrev_b32_e32 v253, 4, v253
	v_lshl_add_u32 v242, v251, 7, v253
	v_xor_b32_e32 v243, 64, v242
	s_mov_b32 s11, 0
	v_and_b32_e32 v244, 15, v208
	v_lshlrev_b32_e32 v244, 2, v244
	s_lshl_b32 s2, s10, 9
	s_add_i32 s2, s2, 0x36c80000
	v_add_u32_e32 v244, s2, v244
	v_mov_b32_e32 v245, s93
	v_add_co_u32_e32 v244, vcc, s92, v244
	s_nop 1
	v_addc_co_u32_e32 v245, vcc, 0, v245, vcc
	global_load_dword v246, v[244:245], off
	global_load_dword v247, v[244:245], off offset:64
	global_load_dword v248, v[244:245], off offset:128
	global_load_dword v249, v[244:245], off offset:192
	global_load_dword v250, v[244:245], off offset:256
	global_load_dword v251, v[244:245], off offset:320
	global_load_dword v252, v[244:245], off offset:384
	global_load_dword v253, v[244:245], off offset:448
	s_getreg_b32 vcc_hi, hwreg(HW_REG_HW_ID, 8, 4)
	s_lshl_b32 s2, s10, 18
	s_add_i32 s2, s2, 0x1e000000
	s_lshl_b32 vcc_lo, vcc_hi, 7
	s_add_i32 s2, s2, vcc_lo
	s_add_u32 s12, s92, s2
	s_addc_u32 s13, s93, 0
	s_add_i32 s2, s11, s10
	s_and_b32 s2, s2, 3
	s_lshl_b32 s2, s2, 19
	s_lshl_b32 s21, s20, 5
	s_add_i32 s2, s2, s21
	s_add_i32 s2, s2, 0x34800000
	s_lshl_b32 vcc_lo, vcc_hi, 11
	s_add_i32 s2, s2, vcc_lo
	s_add_u32 s14, s92, s2
	s_addc_u32 s15, s93, 0
	s_mov_b32 s19, 0
	s_mov_b32 s17, 0
	s_mov_b32 s18, -2
	s_add_i32 m0, s17, s20
	s_nop 0
	global_load_lds_dwordx4 v234, s[12:13]
	s_add_i32 m0, m0, 0x400
	s_nop 0
	global_load_lds_dwordx4 v235, s[12:13]
	s_add_i32 m0, m0, 0x400
	s_nop 0
	global_load_lds_dwordx4 v236, s[12:13]
	s_add_i32 m0, m0, 0x400
	s_nop 0
	global_load_lds_dwordx4 v237, s[12:13]
	s_add_i32 vcc_lo, vcc_hi, s18
	s_add_i32 vcc_lo, vcc_lo, 2
	s_and_b32 vcc_lo, vcc_lo, 15
	s_cmp_eq_u32 vcc_lo, 15
	s_cbranch_scc1 .Lg3_awp0
	s_add_u32 s12, s12, 128
	s_addc_u32 s13, s13, 0
	s_branch .Lg3_axp0
.Lg3_awp0:
	s_sub_u32 s12, s12, 1920
	s_subb_u32 s13, s13, 0
.Lg3_axp0:
	global_load_dwordx4 v[128:131], v238, s[14:15]
	global_load_dwordx4 v[132:135], v239, s[14:15]
	global_load_dwordx4 v[136:139], v240, s[14:15]
	global_load_dwordx4 v[140:143], v241, s[14:15]
	s_lshl_b32 vcc_lo, vcc_hi, 1
	s_add_i32 vcc_lo, vcc_lo, s19
	s_and_b32 vcc_lo, vcc_lo, 31
	s_cmp_eq_u32 vcc_lo, 31
	s_cbranch_scc1 .Lg3_www0
	s_add_u32 s14, s14, 1024
	s_addc_u32 s15, s15, 0
	s_branch .Lg3_wxw0
.Lg3_www0:
	s_sub_u32 s14, s14, 31744
	s_subb_u32 s15, s15, 0
.Lg3_wxw0:
	s_add_i32 s19, s19, 1
	global_load_dwordx4 v[144:147], v238, s[14:15]
	global_load_dwordx4 v[148:151], v239, s[14:15]
	global_load_dwordx4 v[152:155], v240, s[14:15]
	global_load_dwordx4 v[156:159], v241, s[14:15]
	s_lshl_b32 vcc_lo, vcc_hi, 1
	s_add_i32 vcc_lo, vcc_lo, s19
	s_and_b32 vcc_lo, vcc_lo, 31
	s_cmp_eq_u32 vcc_lo, 31
	s_cbranch_scc1 .Lg3_www1
	s_add_u32 s14, s14, 1024
	s_addc_u32 s15, s15, 0
	s_branch .Lg3_wxw1

.Lg3_wxw1:
	s_add_i32 s19, s19, 1
	s_movk_i32 s17, 0x4000
	s_mov_b32 s18, -1
	s_add_i32 m0, s17, s20
	s_nop 0
	global_load_lds_dwordx4 v234, s[12:13]
	s_add_i32 m0, m0, 0x400
	s_nop 0
	global_load_lds_dwordx4 v235, s[12:13]
	s_add_i32 m0, m0, 0x400
	s_nop 0
	global_load_lds_dwordx4 v236, s[12:13]
	s_add_i32 m0, m0, 0x400
	s_nop 0
	global_load_lds_dwordx4 v237, s[12:13]
	s_add_i32 vcc_lo, vcc_hi, s18
	s_add_i32 vcc_lo, vcc_lo, 2
	s_and_b32 vcc_lo, vcc_lo, 15
	s_cmp_eq_u32 vcc_lo, 15
	s_cbranch_scc1 .Lg3_awp1
	s_add_u32 s12, s12, 128
	s_addc_u32 s13, s13, 0
	s_branch .Lg3_axp1

.Lg3_axp1:
	global_load_dwordx4 v[160:163], v238, s[14:15]
	global_load_dwordx4 v[164:167], v239, s[14:15]
	global_load_dwordx4 v[168:171], v240, s[14:15]
	global_load_dwordx4 v[172:175], v241, s[14:15]
	s_lshl_b32 vcc_lo, vcc_hi, 1
	s_add_i32 vcc_lo, vcc_lo, s19
	s_and_b32 vcc_lo, vcc_lo, 31
	s_cmp_eq_u32 vcc_lo, 31
	s_cbranch_scc1 .Lg3_www2
	s_add_u32 s14, s14, 1024
	s_addc_u32 s15, s15, 0
	s_branch .Lg3_wxw2

.Lg3_wxw2:
	s_add_i32 s19, s19, 1
	s_mov_b32 s16, 0
	s_mov_b32 s17, 0x8000
.Lg3_chunk:
	s_getreg_b32 vcc_hi, hwreg(HW_REG_HW_ID, 8, 4)
	v_mov_b32_e32 v0, 0
	v_mov_b32_e32 v1, 0
	v_mov_b32_e32 v2, 0
	v_mov_b32_e32 v3, 0
	v_mov_b32_e32 v4, 0
	v_mov_b32_e32 v5, 0
	v_mov_b32_e32 v6, 0
	v_mov_b32_e32 v7, 0
	v_mov_b32_e32 v8, 0
	v_mov_b32_e32 v9, 0
	v_mov_b32_e32 v10, 0
	v_mov_b32_e32 v11, 0
	v_mov_b32_e32 v12, 0
	v_mov_b32_e32 v13, 0
	v_mov_b32_e32 v14, 0
	v_mov_b32_e32 v15, 0
	v_mov_b32_e32 v16, 0
	v_mov_b32_e32 v17, 0
	v_mov_b32_e32 v18, 0
	v_mov_b32_e32 v19, 0
	v_mov_b32_e32 v20, 0
	v_mov_b32_e32 v21, 0
	v_mov_b32_e32 v22, 0
	v_mov_b32_e32 v23, 0
	v_mov_b32_e32 v24, 0
	v_mov_b32_e32 v25, 0
	v_mov_b32_e32 v26, 0
	v_mov_b32_e32 v27, 0
	v_mov_b32_e32 v28, 0
	v_mov_b32_e32 v29, 0
	v_mov_b32_e32 v30, 0
	v_mov_b32_e32 v31, 0
	v_mov_b32_e32 v32, 0
	v_mov_b32_e32 v33, 0
	v_mov_b32_e32 v34, 0
	v_mov_b32_e32 v35, 0
	v_mov_b32_e32 v36, 0
	v_mov_b32_e32 v37, 0
	v_mov_b32_e32 v38, 0
	v_mov_b32_e32 v39, 0
	v_mov_b32_e32 v40, 0
	v_mov_b32_e32 v41, 0
	v_mov_b32_e32 v42, 0
	v_mov_b32_e32 v43, 0
	v_mov_b32_e32 v44, 0
	v_mov_b32_e32 v45, 0
	v_mov_b32_e32 v46, 0
	v_mov_b32_e32 v47, 0
	v_mov_b32_e32 v48, 0
	v_mov_b32_e32 v49, 0
	v_mov_b32_e32 v50, 0
	v_mov_b32_e32 v51, 0
	v_mov_b32_e32 v52, 0
	v_mov_b32_e32 v53, 0
	v_mov_b32_e32 v54, 0
	v_mov_b32_e32 v55, 0
	v_mov_b32_e32 v56, 0
	v_mov_b32_e32 v57, 0
	v_mov_b32_e32 v58, 0
	v_mov_b32_e32 v59, 0
	v_mov_b32_e32 v60, 0
	v_mov_b32_e32 v61, 0
	v_mov_b32_e32 v62, 0
	v_mov_b32_e32 v63, 0
	v_mov_b32_e32 v64, 0
	v_mov_b32_e32 v65, 0
	v_mov_b32_e32 v66, 0
	v_mov_b32_e32 v67, 0
	v_mov_b32_e32 v68, 0
	v_mov_b32_e32 v69, 0
	v_mov_b32_e32 v70, 0
	v_mov_b32_e32 v71, 0
	v_mov_b32_e32 v72, 0
	v_mov_b32_e32 v73, 0
	v_mov_b32_e32 v74, 0
	v_mov_b32_e32 v75, 0
	v_mov_b32_e32 v76, 0
	v_mov_b32_e32 v77, 0
	v_mov_b32_e32 v78, 0
	v_mov_b32_e32 v79, 0
	v_mov_b32_e32 v80, 0
	v_mov_b32_e32 v81, 0
	v_mov_b32_e32 v82, 0
	v_mov_b32_e32 v83, 0
	v_mov_b32_e32 v84, 0
	v_mov_b32_e32 v85, 0
	v_mov_b32_e32 v86, 0
	v_mov_b32_e32 v87, 0
	v_mov_b32_e32 v88, 0
	v_mov_b32_e32 v89, 0
	v_mov_b32_e32 v90, 0
	v_mov_b32_e32 v91, 0
	v_mov_b32_e32 v92, 0
	v_mov_b32_e32 v93, 0
	v_mov_b32_e32 v94, 0
	v_mov_b32_e32 v95, 0
	v_mov_b32_e32 v96, 0
	v_mov_b32_e32 v97, 0
	v_mov_b32_e32 v98, 0
	v_mov_b32_e32 v99, 0
	v_mov_b32_e32 v100, 0
	v_mov_b32_e32 v101, 0
	v_mov_b32_e32 v102, 0
	v_mov_b32_e32 v103, 0
	v_mov_b32_e32 v104, 0
	v_mov_b32_e32 v105, 0
	v_mov_b32_e32 v106, 0
	v_mov_b32_e32 v107, 0
	v_mov_b32_e32 v108, 0
	v_mov_b32_e32 v109, 0
	v_mov_b32_e32 v110, 0
	v_mov_b32_e32 v111, 0
	v_mov_b32_e32 v112, 0
	v_mov_b32_e32 v113, 0
	v_mov_b32_e32 v114, 0
	v_mov_b32_e32 v115, 0
	v_mov_b32_e32 v116, 0
	v_mov_b32_e32 v117, 0
	v_mov_b32_e32 v118, 0
	v_mov_b32_e32 v119, 0
	v_mov_b32_e32 v120, 0
	v_mov_b32_e32 v121, 0
	v_mov_b32_e32 v122, 0
	v_mov_b32_e32 v123, 0
	v_mov_b32_e32 v124, 0
	v_mov_b32_e32 v125, 0
	v_mov_b32_e32 v126, 0
	v_mov_b32_e32 v127, 0
	s_mov_b32 s19, 3
	s_mov_b32 s18, 0
.Lg3_loop:
	s_waitcnt vmcnt(12)
	s_barrier
	global_load_dwordx4 v[176:179], v238, s[14:15]
	global_load_dwordx4 v[182:185], v239, s[14:15]
	global_load_dwordx4 v[186:189], v240, s[14:15]
	global_load_dwordx4 v[194:197], v241, s[14:15]
	s_cmp_eq_u32 s19, 31
	s_cbranch_scc1 .Lg3_sww3
	s_lshl_b32 vcc_lo, vcc_hi, 1
	s_add_i32 vcc_lo, vcc_lo, s19
	s_and_b32 vcc_lo, vcc_lo, 31
	s_cmp_eq_u32 vcc_lo, 31
	s_cbranch_scc1 .Lg3_www3
	s_add_u32 s14, s14, 1024
	s_addc_u32 s15, s15, 0
	s_branch .Lg3_wxw3

.Lg3_sww3:
	s_cmp_lt_u32 s11, 3
	s_cbranch_scc1 .Lg3_wsamew3
	s_add_i32 s21, s10, s95
	s_cmpk_gt_i32 s21, 0x1ff
	s_cbranch_scc1 .Lg3_wndw3
	s_and_b32 s2, s21, 3
	s_sub_i32 s21, s21, s2
	s_add_i32 s2, s2, s21
	s_and_b32 s2, s2, 3
	s_lshl_b32 s2, s2, 19
	s_lshl_b32 s21, s20, 5
	s_add_i32 s2, s2, s21
	s_add_i32 s2, s2, 0x34800000
	s_lshl_b32 vcc_lo, vcc_hi, 11
	s_add_i32 s2, s2, vcc_lo
	s_add_u32 s14, s92, s2
	s_addc_u32 s15, s93, 0
	s_branch .Lg3_wndw3
.Lg3_wsamew3:
	s_add_i32 s21, s11, 1
	s_add_i32 s2, s21, s10
	s_and_b32 s2, s2, 3
	s_lshl_b32 s2, s2, 19
	s_lshl_b32 s21, s20, 5
	s_add_i32 s2, s2, s21
	s_add_i32 s2, s2, 0x34800000
	s_lshl_b32 vcc_lo, vcc_hi, 11
	s_add_i32 s2, s2, vcc_lo
	s_add_u32 s14, s92, s2
	s_addc_u32 s15, s93, 0
.Lg3_wndw3:
.Lg3_swdw3:
	s_add_i32 s19, s19, 1
	s_add_i32 m0, s17, s20
	s_nop 0
	global_load_lds_dwordx4 v234, s[12:13]
	s_add_i32 m0, m0, 0x400
	s_nop 0
	global_load_lds_dwordx4 v235, s[12:13]
	s_add_i32 m0, m0, 0x400
	s_nop 0
	global_load_lds_dwordx4 v236, s[12:13]
	s_add_i32 m0, m0, 0x400
	s_nop 0
	global_load_lds_dwordx4 v237, s[12:13]
	s_cmp_eq_u32 s18, 13
	s_cbranch_scc1 .Lg3_saa4
	s_add_i32 vcc_lo, vcc_hi, s18
	s_add_i32 vcc_lo, vcc_lo, 2
	s_and_b32 vcc_lo, vcc_lo, 15
	s_cmp_eq_u32 vcc_lo, 15
	s_cbranch_scc1 .Lg3_awa4
	s_add_u32 s12, s12, 128
	s_addc_u32 s13, s13, 0
	s_branch .Lg3_axa4

.Lg3_saa4:
	s_cmp_lt_u32 s11, 3
	s_cbranch_scc1 .Lg3_samea4
	s_add_i32 s21, s10, s95
	s_cmpk_gt_i32 s21, 0x1ff
	s_cbranch_scc1 .Lg3_nda4
	s_lshl_b32 s2, s21, 18
	s_add_i32 s2, s2, 0x1e000000
	s_lshl_b32 vcc_lo, vcc_hi, 7
	s_add_i32 s2, s2, vcc_lo
	s_add_u32 s12, s92, s2
	s_addc_u32 s13, s93, 0
	s_branch .Lg3_nda4
.Lg3_samea4:
	s_lshl_b32 s2, s10, 18
	s_add_i32 s2, s2, 0x1e000000
	s_lshl_b32 vcc_lo, vcc_hi, 7
	s_add_i32 s2, s2, vcc_lo
	s_add_u32 s12, s92, s2
	s_addc_u32 s13, s93, 0
.Lg3_nda4:
.Lg3_sada4:
	v_add_u32_e32 v244, s16, v242
	v_add_u32_e32 v245, s16, v243
	ds_read_b128 v[198:201], v244 offset:0
	ds_read_b128 v[202:205], v244 offset:2048
	ds_read_b128 v[210:213], v244 offset:4096
	ds_read_b128 v[214:217], v244 offset:6144
	ds_read_b128 v[218:221], v244 offset:8192
	ds_read_b128 v[222:225], v244 offset:10240
	ds_read_b128 v[226:229], v244 offset:12288
	ds_read_b128 v[230:233], v244 offset:14336
	s_waitcnt lgkmcnt(4)
	v_mfma_f32_16x16x32_bf16 v[0:3], v[128:131], v[198:201], v[0:3]
	v_mfma_f32_16x16x32_bf16 v[32:35], v[132:135], v[198:201], v[32:35]
	v_mfma_f32_16x16x32_bf16 v[64:67], v[136:139], v[198:201], v[64:67]
	v_mfma_f32_16x16x32_bf16 v[96:99], v[140:143], v[198:201], v[96:99]
	v_mfma_f32_16x16x32_bf16 v[4:7], v[128:131], v[202:205], v[4:7]
	v_mfma_f32_16x16x32_bf16 v[36:39], v[132:135], v[202:205], v[36:39]
	v_mfma_f32_16x16x32_bf16 v[68:71], v[136:139], v[202:205], v[68:71]
	v_mfma_f32_16x16x32_bf16 v[100:103], v[140:143], v[202:205], v[100:103]
	v_mfma_f32_16x16x32_bf16 v[8:11], v[128:131], v[210:213], v[8:11]
	v_mfma_f32_16x16x32_bf16 v[40:43], v[132:135], v[210:213], v[40:43]
	v_mfma_f32_16x16x32_bf16 v[72:75], v[136:139], v[210:213], v[72:75]
	v_mfma_f32_16x16x32_bf16 v[104:107], v[140:143], v[210:213], v[104:107]
	v_mfma_f32_16x16x32_bf16 v[12:15], v[128:131], v[214:217], v[12:15]
	v_mfma_f32_16x16x32_bf16 v[44:47], v[132:135], v[214:217], v[44:47]
	v_mfma_f32_16x16x32_bf16 v[76:79], v[136:139], v[214:217], v[76:79]
	v_mfma_f32_16x16x32_bf16 v[108:111], v[140:143], v[214:217], v[108:111]
	s_waitcnt lgkmcnt(0)
	v_mfma_f32_16x16x32_bf16 v[16:19], v[128:131], v[218:221], v[16:19]
	v_mfma_f32_16x16x32_bf16 v[48:51], v[132:135], v[218:221], v[48:51]
	v_mfma_f32_16x16x32_bf16 v[80:83], v[136:139], v[218:221], v[80:83]
	v_mfma_f32_16x16x32_bf16 v[112:115], v[140:143], v[218:221], v[112:115]
	v_mfma_f32_16x16x32_bf16 v[20:23], v[128:131], v[222:225], v[20:23]
	v_mfma_f32_16x16x32_bf16 v[52:55], v[132:135], v[222:225], v[52:55]
	v_mfma_f32_16x16x32_bf16 v[84:87], v[136:139], v[222:225], v[84:87]
	v_mfma_f32_16x16x32_bf16 v[116:119], v[140:143], v[222:225], v[116:119]
	v_mfma_f32_16x16x32_bf16 v[24:27], v[128:131], v[226:229], v[24:27]
	v_mfma_f32_16x16x32_bf16 v[56:59], v[132:135], v[226:229], v[56:59]
	v_mfma_f32_16x16x32_bf16 v[88:91], v[136:139], v[226:229], v[88:91]
	v_mfma_f32_16x16x32_bf16 v[120:123], v[140:143], v[226:229], v[120:123]
	v_mfma_f32_16x16x32_bf16 v[28:31], v[128:131], v[230:233], v[28:31]
	v_mfma_f32_16x16x32_bf16 v[60:63], v[132:135], v[230:233], v[60:63]
	v_mfma_f32_16x16x32_bf16 v[92:95], v[136:139], v[230:233], v[92:95]
	v_mfma_f32_16x16x32_bf16 v[124:127], v[140:143], v[230:233], v[124:127]
	s_waitcnt vmcnt(16)
	global_load_dwordx4 v[128:131], v238, s[14:15]
	global_load_dwordx4 v[132:135], v239, s[14:15]
	global_load_dwordx4 v[136:139], v240, s[14:15]
	global_load_dwordx4 v[140:143], v241, s[14:15]
	s_cmp_eq_u32 s19, 31
	s_cbranch_scc1 .Lg3_sww5
	s_lshl_b32 vcc_lo, vcc_hi, 1
	s_add_i32 vcc_lo, vcc_lo, s19
	s_and_b32 vcc_lo, vcc_lo, 31
	s_cmp_eq_u32 vcc_lo, 31
	s_cbranch_scc1 .Lg3_www5
	s_add_u32 s14, s14, 1024
	s_addc_u32 s15, s15, 0
	s_branch .Lg3_wxw5

.Lg3_wndw5:
.Lg3_swdw5:
	s_add_i32 s19, s19, 1
	ds_read_b128 v[198:201], v245 offset:0
	ds_read_b128 v[202:205], v245 offset:2048
	ds_read_b128 v[210:213], v245 offset:4096
	ds_read_b128 v[214:217], v245 offset:6144
	ds_read_b128 v[218:221], v245 offset:8192
	ds_read_b128 v[222:225], v245 offset:10240
	ds_read_b128 v[226:229], v245 offset:12288
	ds_read_b128 v[230:233], v245 offset:14336
	s_waitcnt lgkmcnt(4)
	v_mfma_f32_16x16x32_bf16 v[0:3], v[144:147], v[198:201], v[0:3]
	v_mfma_f32_16x16x32_bf16 v[32:35], v[148:151], v[198:201], v[32:35]
	v_mfma_f32_16x16x32_bf16 v[64:67], v[152:155], v[198:201], v[64:67]
	v_mfma_f32_16x16x32_bf16 v[96:99], v[156:159], v[198:201], v[96:99]
	v_mfma_f32_16x16x32_bf16 v[4:7], v[144:147], v[202:205], v[4:7]
	v_mfma_f32_16x16x32_bf16 v[36:39], v[148:151], v[202:205], v[36:39]
	v_mfma_f32_16x16x32_bf16 v[68:71], v[152:155], v[202:205], v[68:71]
	v_mfma_f32_16x16x32_bf16 v[100:103], v[156:159], v[202:205], v[100:103]
	v_mfma_f32_16x16x32_bf16 v[8:11], v[144:147], v[210:213], v[8:11]
	v_mfma_f32_16x16x32_bf16 v[40:43], v[148:151], v[210:213], v[40:43]
	v_mfma_f32_16x16x32_bf16 v[72:75], v[152:155], v[210:213], v[72:75]
	v_mfma_f32_16x16x32_bf16 v[104:107], v[156:159], v[210:213], v[104:107]
	v_mfma_f32_16x16x32_bf16 v[12:15], v[144:147], v[214:217], v[12:15]
	v_mfma_f32_16x16x32_bf16 v[44:47], v[148:151], v[214:217], v[44:47]
	v_mfma_f32_16x16x32_bf16 v[76:79], v[152:155], v[214:217], v[76:79]
	v_mfma_f32_16x16x32_bf16 v[108:111], v[156:159], v[214:217], v[108:111]
	s_waitcnt lgkmcnt(0)
	v_mfma_f32_16x16x32_bf16 v[16:19], v[144:147], v[218:221], v[16:19]
	v_mfma_f32_16x16x32_bf16 v[48:51], v[148:151], v[218:221], v[48:51]
	v_mfma_f32_16x16x32_bf16 v[80:83], v[152:155], v[218:221], v[80:83]
	v_mfma_f32_16x16x32_bf16 v[112:115], v[156:159], v[218:221], v[112:115]
	v_mfma_f32_16x16x32_bf16 v[20:23], v[144:147], v[222:225], v[20:23]
	v_mfma_f32_16x16x32_bf16 v[52:55], v[148:151], v[222:225], v[52:55]
	v_mfma_f32_16x16x32_bf16 v[84:87], v[152:155], v[222:225], v[84:87]
	v_mfma_f32_16x16x32_bf16 v[116:119], v[156:159], v[222:225], v[116:119]
	v_mfma_f32_16x16x32_bf16 v[24:27], v[144:147], v[226:229], v[24:27]
	v_mfma_f32_16x16x32_bf16 v[56:59], v[148:151], v[226:229], v[56:59]
	v_mfma_f32_16x16x32_bf16 v[88:91], v[152:155], v[226:229], v[88:91]
	v_mfma_f32_16x16x32_bf16 v[120:123], v[156:159], v[226:229], v[120:123]
	v_mfma_f32_16x16x32_bf16 v[28:31], v[144:147], v[230:233], v[28:31]
	v_mfma_f32_16x16x32_bf16 v[60:63], v[148:151], v[230:233], v[60:63]
	v_mfma_f32_16x16x32_bf16 v[92:95], v[152:155], v[230:233], v[92:95]
	v_mfma_f32_16x16x32_bf16 v[124:127], v[156:159], v[230:233], v[124:127]
	s_add_i32 s16, s16, 0x4000
	s_cmp_lt_u32 s16, 0xc000
	s_cselect_b32 s16, s16, 0
	s_add_i32 s17, s17, 0x4000
	s_cmp_lt_u32 s17, 0xc000
	s_cselect_b32 s17, s17, 0
	s_add_i32 s18, s18, 1
	s_waitcnt vmcnt(12)
	s_barrier
	global_load_dwordx4 v[144:147], v238, s[14:15]
	global_load_dwordx4 v[148:151], v239, s[14:15]
	global_load_dwordx4 v[152:155], v240, s[14:15]
	global_load_dwordx4 v[156:159], v241, s[14:15]
	s_cmp_eq_u32 s19, 31
	s_cbranch_scc1 .Lg3_sww6
	s_lshl_b32 vcc_lo, vcc_hi, 1
	s_add_i32 vcc_lo, vcc_lo, s19
	s_and_b32 vcc_lo, vcc_lo, 31
	s_cmp_eq_u32 vcc_lo, 31
	s_cbranch_scc1 .Lg3_www6
	s_add_u32 s14, s14, 1024
	s_addc_u32 s15, s15, 0
	s_branch .Lg3_wxw6

.Lg3_nda7:
.Lg3_sada7:
	v_add_u32_e32 v244, s16, v242
	v_add_u32_e32 v245, s16, v243
	ds_read_b128 v[198:201], v244 offset:0
	ds_read_b128 v[202:205], v244 offset:2048
	ds_read_b128 v[210:213], v244 offset:4096
	ds_read_b128 v[214:217], v244 offset:6144
	ds_read_b128 v[218:221], v244 offset:8192
	ds_read_b128 v[222:225], v244 offset:10240
	ds_read_b128 v[226:229], v244 offset:12288
	ds_read_b128 v[230:233], v244 offset:14336
	s_waitcnt lgkmcnt(4)
	v_mfma_f32_16x16x32_bf16 v[0:3], v[160:163], v[198:201], v[0:3]
	v_mfma_f32_16x16x32_bf16 v[32:35], v[164:167], v[198:201], v[32:35]
	v_mfma_f32_16x16x32_bf16 v[64:67], v[168:171], v[198:201], v[64:67]
	v_mfma_f32_16x16x32_bf16 v[96:99], v[172:175], v[198:201], v[96:99]
	v_mfma_f32_16x16x32_bf16 v[4:7], v[160:163], v[202:205], v[4:7]
	v_mfma_f32_16x16x32_bf16 v[36:39], v[164:167], v[202:205], v[36:39]
	v_mfma_f32_16x16x32_bf16 v[68:71], v[168:171], v[202:205], v[68:71]
	v_mfma_f32_16x16x32_bf16 v[100:103], v[172:175], v[202:205], v[100:103]
	v_mfma_f32_16x16x32_bf16 v[8:11], v[160:163], v[210:213], v[8:11]
	v_mfma_f32_16x16x32_bf16 v[40:43], v[164:167], v[210:213], v[40:43]
	v_mfma_f32_16x16x32_bf16 v[72:75], v[168:171], v[210:213], v[72:75]
	v_mfma_f32_16x16x32_bf16 v[104:107], v[172:175], v[210:213], v[104:107]
	v_mfma_f32_16x16x32_bf16 v[12:15], v[160:163], v[214:217], v[12:15]
	v_mfma_f32_16x16x32_bf16 v[44:47], v[164:167], v[214:217], v[44:47]
	v_mfma_f32_16x16x32_bf16 v[76:79], v[168:171], v[214:217], v[76:79]
	v_mfma_f32_16x16x32_bf16 v[108:111], v[172:175], v[214:217], v[108:111]
	s_waitcnt lgkmcnt(0)
	v_mfma_f32_16x16x32_bf16 v[16:19], v[160:163], v[218:221], v[16:19]
	v_mfma_f32_16x16x32_bf16 v[48:51], v[164:167], v[218:221], v[48:51]
	v_mfma_f32_16x16x32_bf16 v[80:83], v[168:171], v[218:221], v[80:83]
	v_mfma_f32_16x16x32_bf16 v[112:115], v[172:175], v[218:221], v[112:115]
	v_mfma_f32_16x16x32_bf16 v[20:23], v[160:163], v[222:225], v[20:23]
	v_mfma_f32_16x16x32_bf16 v[52:55], v[164:167], v[222:225], v[52:55]
	v_mfma_f32_16x16x32_bf16 v[84:87], v[168:171], v[222:225], v[84:87]
	v_mfma_f32_16x16x32_bf16 v[116:119], v[172:175], v[222:225], v[116:119]
	v_mfma_f32_16x16x32_bf16 v[24:27], v[160:163], v[226:229], v[24:27]
	v_mfma_f32_16x16x32_bf16 v[56:59], v[164:167], v[226:229], v[56:59]
	v_mfma_f32_16x16x32_bf16 v[88:91], v[168:171], v[226:229], v[88:91]
	v_mfma_f32_16x16x32_bf16 v[120:123], v[172:175], v[226:229], v[120:123]
	v_mfma_f32_16x16x32_bf16 v[28:31], v[160:163], v[230:233], v[28:31]
	v_mfma_f32_16x16x32_bf16 v[60:63], v[164:167], v[230:233], v[60:63]
	v_mfma_f32_16x16x32_bf16 v[92:95], v[168:171], v[230:233], v[92:95]
	v_mfma_f32_16x16x32_bf16 v[124:127], v[172:175], v[230:233], v[124:127]
	s_waitcnt vmcnt(16)
	global_load_dwordx4 v[160:163], v238, s[14:15]
	global_load_dwordx4 v[164:167], v239, s[14:15]
	global_load_dwordx4 v[168:171], v240, s[14:15]
	global_load_dwordx4 v[172:175], v241, s[14:15]
	s_cmp_eq_u32 s19, 31
	s_cbranch_scc1 .Lg3_sww8
	s_lshl_b32 vcc_lo, vcc_hi, 1
	s_add_i32 vcc_lo, vcc_lo, s19
	s_and_b32 vcc_lo, vcc_lo, 31
	s_cmp_eq_u32 vcc_lo, 31
	s_cbranch_scc1 .Lg3_www8
	s_add_u32 s14, s14, 1024
	s_addc_u32 s15, s15, 0
	s_branch .Lg3_wxw8
